# v110 + P2 step 4 hand-written (six ds_read_b128 up front, branch-free selects, instead of element-wise exec-masked LDS round trips)
# speedup vs baseline: 1.0132x; 1.0019x over previous
; #define LAS __attribute__((address_space(3)))
; __device__ __forceinline__ u32x2_t pack4bf(f32x4 v) { u32x2_t r; r.x = pg8::cvt_pk_bf16(v[0], v[1]); r.y = pg8::cvt_pk_bf16(v[2], v[3]); return r; }
; __device__ __forceinline__ int frag_off(int row, int k, int ksteps) { return ((row >> 4) * ksteps + (k >> 5)) * 512 + (((k >> 3) & 3) * 16 + (row & 15)) * 8 + (k & 7); }
; __device__ __forceinline__ int ut_off(int d, int i) { return (((d >> 5) * 4 + (i >> 4)) * 64 + ((i >> 2) & 3) * 16 + (d & 15)) * 8 + ((d >> 4) & 1) * 4 + (i & 3); }
; template <int SKIP>
; __device__ __forceinline__ void p2_chunk_prep_fast(Frame& F, const Args& a) {
;     ...
;         if (!(SKIP & 16)) {
;             bf16_t *oU = UT + (size_t)cu * 8192, *oNW = NW + (size_t)cu * 8192;
;             bf16x8_t vf[2], kf[2];
; #pragma unroll
;             for (int ks = 0; ks < 2; ++ks) { vf[ks] = *(const LAS bf16x8_t*)(L + L_VT + ktoff(16 * w + fr, 4 * ks + fq)); kf[ks] = *(const LAS bf16x8_t*)(L + L_KT + ktoff(16 * w + fr, 4 * ks + fq)); }
; #pragma unroll
;             for (int mi = 0; mi < 4; ++mi) {
;                 f32x4 au = (f32x4){0.f, 0.f, 0.f, 0.f}, aw = (f32x4){0.f, 0.f, 0.f, 0.f};
; #pragma unroll
;                 for (int ks = 0; ks < 2; ++ks) {
;                     au = __builtin_amdgcn_mfma_f32_16x16x32_bf16(*(const LAS bf16x8_t*)(L + L_TB + (16 * mi + fr) * KT_LD + (32 * ks + 8 * fq) * 2), vf[ks], au, 0, 0, 0);
;                     aw = __builtin_amdgcn_mfma_f32_16x16x32_bf16(kf[ks], *(const LAS bf16x8_t*)(L + L_TW + (16 * mi + fr) * KT_LD + (32 * ks + 8 * fq) * 2), aw, 0, 0, 0);
;                 }
;                 *(u32x2_t*)(oU + ut_off(16 * w + fr, 16 * mi + 4 * fq)) = pack4bf(au);
;                 *(u32x2_t*)(oNW + frag_off(16 * mi + fr, 16 * w + 4 * fq, 4)) = pack4bf(-aw);
;             }
;         }
.LBB0_611:
	v_add_u32_e32 v77, s40, v66
	v_add_u32_e32 v76, s31, v66
	v_lshrrev_b32_e32 v67, 4, v67
	s_lshl_b64 s[84:85], s[86:87], 1
	v_readlane_b32 s6, v255, 28
	v_and_b32_e32 v78, 0x1f8, v63
	s_add_u32 s6, s6, s84
	v_readlane_b32 s7, v255, 33
	s_addc_u32 s7, s7, s85
	v_readlane_b32 s86, v255, 23
	s_add_u32 s84, s86, s84
	v_mad_u32_u24 v65, v83, s30, v77
	v_readlane_b32 s86, v255, 27
	s_addc_u32 s85, s86, s85
	s_andn2_b64 vcc, exec, s[8:9]
	v_or_b32_e32 v46, s54, v83
	v_mul_lo_u32 v47, v46, s30
	v_lshrrev_b32_e32 v46, 3, v46
	v_bitop3_b32 v48, v46, v118, 7 bitop3:0x6c
	v_lshlrev_b32_e32 v48, 4, v48
	v_add3_u32 v48, v48, v47, 0
	s_waitcnt lgkmcnt(0)
	s_barrier
	ds_read_b128 v[58:61], v48 offset:53248
	ds_read_b128 v[54:57], v48 offset:34816
	v_add_u32_e32 v48, 4, v118
	v_lshlrev_b32_e32 v64, 1, v69
	v_bitop3_b32 v46, v46, v48, 7 bitop3:0x6c
	v_lshlrev_b32_e32 v62, 4, v69
	v_and_or_b32 v64, v64, 48, v83
	v_lshlrev_b32_e32 v46, 4, v46
	v_and_b32_e32 v62, 0xfffffe00, v62
	v_lshlrev_b32_e32 v64, 3, v64
	v_add3_u32 v46, v46, v47, 0
	v_or3_b32 v62, v64, v62, v68
	v_mad_u32_u24 v64, v83, s30, v76
	ds_read_b128 v[50:53], v46 offset:53248
	ds_read_b128 v[46:49], v46 offset:34816
	ds_read_b128 v[68:71], v64
	ds_read_b128 v[84:87], v64 offset:64
	s_waitcnt lgkmcnt(1)
	v_mfma_f32_16x16x32_bf16 v[68:71], v[68:71], v[58:61], 0
	ds_read_b128 v[72:75], v65
	s_waitcnt lgkmcnt(1)
	v_mfma_f32_16x16x32_bf16 v[68:71], v[84:87], v[50:53], v[68:71]
	ds_read_b128 v[84:87], v65 offset:64
	s_waitcnt lgkmcnt(1)
	v_mfma_f32_16x16x32_bf16 v[72:75], v[54:57], v[72:75], 0
	s_waitcnt lgkmcnt(0)
	v_mfma_f32_16x16x32_bf16 v[72:75], v[46:49], v[84:87], v[72:75]
	s_nop 2
	v_cvt_pk_bf16_f32 v64, v68, v69
	v_add_lshl_u32 v68, v67, s35, 9
	v_or3_b32 v68, v68, v78, s11
	v_ashrrev_i32_e32 v69, 31, v68
	v_cvt_pk_bf16_f32 v65, v70, v71
	v_lshl_add_u64 v[68:69], v[68:69], 1, s[6:7]
	global_store_dwordx2 v[68:69], v[64:65], off
	v_xor_b32_e32 v63, 0x80000000, v75
	v_xor_b32_e32 v65, 0x80000000, v74
	v_xor_b32_e32 v64, 0x80000000, v73
	v_xor_b32_e32 v68, 0x80000000, v72
	v_cvt_pk_bf16_f32 v65, v65, v63
	v_ashrrev_i32_e32 v63, 31, v62
	v_cvt_pk_bf16_f32 v64, v68, v64
	v_lshl_add_u64 v[68:69], v[62:63], 1, s[84:85]
	v_mad_u32_u24 v63, v83, s30, v114
	global_store_dwordx2 v[68:69], v[64:65], off
	v_add_u32_e32 v64, v76, v63
	ds_read_b128 v[68:71], v64
	v_add_u32_e32 v64, v77, v63
	ds_read_b128 v[72:75], v64
	v_add3_u32 v64, s31, v63, v66
	ds_read_b128 v[84:87], v64 offset:64
	s_waitcnt lgkmcnt(2)
	v_mfma_f32_16x16x32_bf16 v[68:71], v[68:71], v[58:61], 0
	v_add3_u32 v63, s40, v63, v66
	s_waitcnt lgkmcnt(0)
	v_mfma_f32_16x16x32_bf16 v[68:71], v[84:87], v[50:53], v[68:71]
	ds_read_b128 v[84:87], v63 offset:64
	v_add_lshl_u32 v63, s78, v67, 9
	v_mfma_f32_16x16x32_bf16 v[72:75], v[54:57], v[72:75], 0
	s_waitcnt lgkmcnt(0)
	v_mfma_f32_16x16x32_bf16 v[72:75], v[46:49], v[84:87], v[72:75]
	s_nop 2
	v_cvt_pk_bf16_f32 v64, v68, v69
	v_or3_b32 v68, v63, v78, s11
	v_ashrrev_i32_e32 v69, 31, v68
	v_cvt_pk_bf16_f32 v65, v70, v71
	v_lshl_add_u64 v[68:69], v[68:69], 1, s[6:7]
	global_store_dwordx2 v[68:69], v[64:65], off
	v_xor_b32_e32 v64, 0x80000000, v73
	v_xor_b32_e32 v68, 0x80000000, v72
	v_cvt_pk_bf16_f32 v64, v68, v64
	v_add_u32_e32 v68, 0x800, v62
	v_xor_b32_e32 v63, 0x80000000, v75
	v_xor_b32_e32 v65, 0x80000000, v74
	v_ashrrev_i32_e32 v69, 31, v68
	v_cvt_pk_bf16_f32 v65, v65, v63
	v_lshl_add_u64 v[68:69], v[68:69], 1, s[84:85]
	v_mad_u32_u24 v63, v83, s30, v115
	global_store_dwordx2 v[68:69], v[64:65], off
	v_add_u32_e32 v64, v76, v63
	ds_read_b128 v[68:71], v64
	v_add_u32_e32 v64, v77, v63
	ds_read_b128 v[72:75], v64
	v_add3_u32 v64, s31, v63, v66
	ds_read_b128 v[84:87], v64 offset:64
	s_waitcnt lgkmcnt(2)
	v_mfma_f32_16x16x32_bf16 v[68:71], v[68:71], v[58:61], 0
	v_add3_u32 v63, s40, v63, v66
	s_waitcnt lgkmcnt(0)
	v_mfma_f32_16x16x32_bf16 v[68:71], v[84:87], v[50:53], v[68:71]
	ds_read_b128 v[84:87], v63 offset:64
	v_add_lshl_u32 v63, v67, s79, 9
	v_mfma_f32_16x16x32_bf16 v[72:75], v[54:57], v[72:75], 0
	s_waitcnt lgkmcnt(0)
	v_mfma_f32_16x16x32_bf16 v[72:75], v[46:49], v[84:87], v[72:75]
	s_nop 2
	v_cvt_pk_bf16_f32 v64, v68, v69
	v_or3_b32 v68, v63, v78, s11
	v_ashrrev_i32_e32 v69, 31, v68
	v_cvt_pk_bf16_f32 v65, v70, v71
	v_lshl_add_u64 v[68:69], v[68:69], 1, s[6:7]
	global_store_dwordx2 v[68:69], v[64:65], off
	v_xor_b32_e32 v64, 0x80000000, v73
	v_xor_b32_e32 v68, 0x80000000, v72
	v_cvt_pk_bf16_f32 v64, v68, v64
	v_add_u32_e32 v68, 0x1000, v62
	v_xor_b32_e32 v63, 0x80000000, v75
	v_xor_b32_e32 v65, 0x80000000, v74
	v_ashrrev_i32_e32 v69, 31, v68
	v_cvt_pk_bf16_f32 v65, v65, v63
	v_lshl_add_u64 v[68:69], v[68:69], 1, s[84:85]
	v_mad_u32_u24 v63, v83, s30, v116
	global_store_dwordx2 v[68:69], v[64:65], off
	v_add_u32_e32 v64, v76, v63
	ds_read_b128 v[68:71], v64
	v_add_u32_e32 v64, v77, v63
	s_waitcnt lgkmcnt(0)
	v_mfma_f32_16x16x32_bf16 v[58:61], v[68:71], v[58:61], 0
	ds_read_b128 v[68:71], v64
	v_add3_u32 v64, s31, v63, v66
	s_waitcnt lgkmcnt(0)
	v_mfma_f32_16x16x32_bf16 v[54:57], v[54:57], v[68:71], 0
	ds_read_b128 v[68:71], v64 offset:64
	s_waitcnt lgkmcnt(0)
	v_mfma_f32_16x16x32_bf16 v[50:53], v[68:71], v[50:53], v[58:61]
	s_nop 2
	v_add3_u32 v58, s40, v63, v66
	ds_read_b128 v[58:61], v58 offset:64
	s_nop 2
	v_cvt_pk_bf16_f32 v50, v50, v51
	s_waitcnt lgkmcnt(0)
	v_mfma_f32_16x16x32_bf16 v[46:49], v[46:49], v[58:61], v[54:57]
	v_cvt_pk_bf16_f32 v51, v52, v53
	v_add_lshl_u32 v52, v67, s77, 9
	v_or3_b32 v52, v52, v78, s11
	s_nop 4
	v_xor_b32_e32 v49, 0x80000000, v49
	v_xor_b32_e32 v48, 0x80000000, v48
	v_xor_b32_e32 v47, 0x80000000, v47
	v_xor_b32_e32 v46, 0x80000000, v46
	v_cvt_pk_bf16_f32 v46, v46, v47
	v_cvt_pk_bf16_f32 v47, v48, v49
	v_add_u32_e32 v48, 0x1800, v62
	v_ashrrev_i32_e32 v53, 31, v52
	v_ashrrev_i32_e32 v49, 31, v48
	v_lshl_add_u64 v[52:53], v[52:53], 1, s[6:7]
	v_lshl_add_u64 v[48:49], v[48:49], 1, s[84:85]
	s_mov_b32 s84, s59
	global_store_dwordx2 v[52:53], v[50:51], off
	global_store_dwordx2 v[48:49], v[46:47], off
	s_barrier
	s_cbranch_vccz .LBB0_723

; __device__ __forceinline__ u32x4 pack8(f32x4 v0, f32x4 v1) { u32x4 w; w.x = cvt_pk_bf16(v0[0], v0[1]); w.y = cvt_pk_bf16(v0[2], v0[3]); w.z = cvt_pk_bf16(v1[0], v1[1]); w.w = cvt_pk_bf16(v1[2], v1[3]); return w; }
; #define LAS __attribute__((address_space(3)))
; template <int SKIP>
; __device__ __forceinline__ void p2_chunk_prep_fast(Frame& F, const Args& a) {
;     ...
;         if (!(SKIP & 16)) { const int i = tid >> 3, j8 = (tid & 7) * 8; f32x4 t0 = *(const LAS f32x4*)(Tm + i * AM_LD + j8), t1 = *(const LAS f32x4*)(Tm + i * AM_LD + j8 + 4); f32x4 b0, b1, w0, w1;
; #pragma unroll
;             for (int j = 0; j < 4; ++j) { const int ja = j8 + j, jb = j8 + 4 + j; const float ba = beta[ja], bb = beta[jb];
;                 b0[j] = ja <= i ? t0[j] * ba : 0.f; b1[j] = jb <= i ? t1[j] * bb : 0.f; w0[j] = b0[j] * __expf(gc[ja]); w1[j] = b1[j] * __expf(gc[jb]); }
;             *(LAS pg8::u32x4*)(L + L_TB + i * KT_LD + j8 * 2) = pg8::pack8(b0, b1); *(LAS pg8::u32x4*)(L + L_TW + i * KT_LD + j8 * 2) = pg8::pack8(w0, w1); }
.LBB0_715:
	v_lshlrev_b32_e32 v63, 3, v117
	v_and_b32_e32 v55, 56, v63
	v_ashrrev_i32_e32 v54, 3, v82
	v_or_b32_e32 v61, 4, v55
	v_mul_lo_u32 v46, v54, s28
	v_lshlrev_b32_e32 v47, 2, v55
	v_lshl_add_u32 v56, v61, 2, 0
	v_add3_u32 v46, s60, v46, v47
	v_add_u32_e32 v56, 0x20400, v56
	s_waitcnt lgkmcnt(0)
	s_barrier
	v_lshrrev_b32_e32 v176, 3, v0
	v_and_b32_e32 v177, 7, v0
	v_lshlrev_b32_e32 v177, 3, v177
	v_lshlrev_b32_e32 v178, 2, v177
	v_mad_u32_u24 v178, v176, s28, v178
	v_add_u32_e32 v178, s60, v178
	v_lshlrev_b32_e32 v179, 2, v177
	v_add_u32_e32 v179, 0x20400, v179
	ds_read_b128 v[120:123], v179 offset:256
	ds_read_b128 v[124:127], v179 offset:272
	ds_read_b128 v[84:87], v178
	ds_read_b128 v[88:91], v178 offset:16
	ds_read_b128 v[92:95], v179
	ds_read_b128 v[96:99], v179 offset:16
	v_sub_u32_e32 v180, v176, v177
	v_lshlrev_b32_e32 v179, 1, v177
	v_mad_u32_u24 v179, v176, s30, v179
	v_add_u32_e32 v178, s31, v179
	v_add_u32_e32 v179, s40, v179
	s_waitcnt lgkmcnt(4)
	v_mul_f32_e32 v120, 0x3fb8aa3b, v120
	v_mul_f32_e32 v121, 0x3fb8aa3b, v121
	v_mul_f32_e32 v122, 0x3fb8aa3b, v122
	v_mul_f32_e32 v123, 0x3fb8aa3b, v123
	v_mul_f32_e32 v124, 0x3fb8aa3b, v124
	v_mul_f32_e32 v125, 0x3fb8aa3b, v125
	v_mul_f32_e32 v126, 0x3fb8aa3b, v126
	v_mul_f32_e32 v127, 0x3fb8aa3b, v127
	v_exp_f32_e32 v120, v120
	v_exp_f32_e32 v121, v121
	v_exp_f32_e32 v122, v122
	v_exp_f32_e32 v123, v123
	v_exp_f32_e32 v124, v124
	v_exp_f32_e32 v125, v125
	v_exp_f32_e32 v126, v126
	v_exp_f32_e32 v127, v127
	s_waitcnt lgkmcnt(0)
	v_cmp_le_i32_e64 s[88:89], 0, v180
	v_cmp_le_i32_e64 s[90:91], 1, v180
	v_cmp_le_i32_e64 s[92:93], 2, v180
	v_cmp_le_i32_e64 s[94:95], 3, v180
	v_mul_f32_e32 v128, v84, v92
	v_mul_f32_e32 v129, v85, v93
	v_mul_f32_e32 v130, v86, v94
	v_mul_f32_e32 v131, v87, v95
	v_cndmask_b32_e64 v128, 0, v128, s[88:89]
	v_cndmask_b32_e64 v129, 0, v129, s[90:91]
	v_cndmask_b32_e64 v130, 0, v130, s[92:93]
	v_cndmask_b32_e64 v131, 0, v131, s[94:95]
	v_cmp_le_i32_e64 s[88:89], 4, v180
	v_cmp_le_i32_e64 s[90:91], 5, v180
	v_cmp_le_i32_e64 s[92:93], 6, v180
	v_cmp_le_i32_e64 s[94:95], 7, v180
	v_mul_f32_e32 v132, v88, v96
	v_mul_f32_e32 v133, v89, v97
	v_mul_f32_e32 v134, v90, v98
	v_mul_f32_e32 v135, v91, v99
	v_cndmask_b32_e64 v132, 0, v132, s[88:89]
	v_cndmask_b32_e64 v133, 0, v133, s[90:91]
	v_cndmask_b32_e64 v134, 0, v134, s[92:93]
	v_cndmask_b32_e64 v135, 0, v135, s[94:95]
	v_mul_f32_e32 v160, v128, v120
	v_mul_f32_e32 v161, v129, v121
	v_mul_f32_e32 v162, v130, v122
	v_mul_f32_e32 v163, v131, v123
	v_mul_f32_e32 v164, v132, v124
	v_mul_f32_e32 v165, v133, v125
	v_mul_f32_e32 v166, v134, v126
	v_mul_f32_e32 v167, v135, v127
	v_cvt_pk_bf16_f32 v168, v128, v129
	v_cvt_pk_bf16_f32 v169, v130, v131
	v_cvt_pk_bf16_f32 v170, v132, v133
	v_cvt_pk_bf16_f32 v171, v134, v135
	v_cvt_pk_bf16_f32 v172, v160, v161
	v_cvt_pk_bf16_f32 v173, v162, v163
	v_cvt_pk_bf16_f32 v174, v164, v165
	v_cvt_pk_bf16_f32 v175, v166, v167
	ds_write_b128 v178, v[168:171]
	ds_write_b128 v179, v[172:175]
	s_branch .LBB0_611
